# RWKV-7 scan compute waves: hand-scheduled 8-step unrolled block (immediate LDS offsets, branch-free y store, interleaved DPP reductions)
# speedup vs baseline: 1.0505x; 1.0505x over previous
; __global__ void __launch_bounds__(NTHR) mega(Params p) {
;     ...
;               const float* cbuf = buf + (ck & 1) * 32 * 340;
;               float* yb = ybuf + (ck & 1) * 512;
;               f32x2 sA = {s0, s1}, sB = {s2, s3};
;               float4 dr = *(const float4*)(cbuf + 4 * kg), dd = *(const float4*)(cbuf + 64 + 4 * kg);
;               float4 kp = *(const float4*)(cbuf + 128 + 4 * kg), nk = *(const float4*)(cbuf + 192 + 4 * kg);
;               float4 ka = *(const float4*)(cbuf + 256 + 4 * kg);
;               float vv = cbuf[320 + row];
;               float2 cc = *(const float2*)(cbuf + 336);
; #pragma unroll 2
;               for (int st = 0; st < 32; ++st) {
;                 const float* sn = cbuf + ((st + 1) & 31) * 340;
;                 const float4 dr2 = *(const float4*)(sn + 4 * kg), dd2 = *(const float4*)(sn + 64 + 4 * kg);
;                 const float4 kp2 = *(const float4*)(sn + 128 + 4 * kg), nk2 = *(const float4*)(sn + 192 + 4 * kg);
;                 const float4 ka2 = *(const float4*)(sn + 256 + 4 * kg);
;                 const float vv2 = sn[320 + row];
;                 const float2 cc2 = *(const float2*)(sn + 336);
;                 const f32x2 nkA = {nk.x, nk.y}, nkB = {nk.z, nk.w}, drA = {dr.x, dr.y}, drB = {dr.z, dr.w};
;                 const f32x2 ddA = {dd.x, dd.y}, ddB = {dd.z, dd.w}, kpA = {kp.x, kp.y}, kpB = {kp.z, kp.w};
;                 const f32x2 kaA = {ka.x, ka.y}, kaB = {ka.z, ka.w};
;                 const f32x2 v2 = {vv, vv};
;                 f32x2 pa = sA * nkA; pa = sB * nkB + pa;
;                 f32x2 py = sA * drA; py = sB * drB + py;
;                 f32x2 tA = v2 * kpA; tA = sA * ddA + tA;
;                 f32x2 tB = v2 * kpB; tB = sB * ddB + tB;
;                 float sa = row16_sum(pa.x + pa.y);
;                 const float yy = row16_sum(py.x + py.y);
;                 const f32x2 sa2 = {sa, sa};
;                 sA = sa2 * kaA + tA;
;                 sB = sa2 * kaB + tB;
;                 if (kg == 0) yb[st * 16 + row] = yy + sa * cc.x + vv * cc.y;
;                 dr = dr2; dd = dd2; kp = kp2; nk = nk2; ka = ka2; vv = vv2; cc = cc2;
;               }
.LBB0_1708:
	s_and_saveexec_b64 s[42:43], s[4:5]
	s_xor_b64 s[68:69], exec, s[42:43]
	s_cbranch_execz .LBB0_1715
	s_and_b32 s42, s95, 1
	s_mul_i32 s66, s42, 0xaa00
	s_lshl_b32 s42, s42, 11
	s_add_i32 s42, s42, 0x15400
	v_lshl_add_u32 v2, v53, 2, s66
	v_lshl_add_u32 v3, v51, 2, s66
	v_mov_b32_e32 v4, s66
	ds_read_b128 v[20:23], v2 offset:768
	ds_read_b128 v[8:11], v2 offset:0
	ds_read_b128 v[12:15], v2 offset:256
	ds_read_b32 v28, v3 offset:1280
	ds_read_b128 v[16:19], v2 offset:512
	ds_read_b128 v[24:27], v2 offset:1024
	ds_read_b64 v[30:31], v4 offset:1344
	v_add_u32_e32 v6, s42, v80
	v_lshlrev_b32_e32 v7, 2, v171
	v_add_u32_e32 v7, 0x17000, v7
	v_cndmask_b32_e64 v5, v7, v6, s[10:11]
	s_waitcnt lgkmcnt(0)
	s_mov_b32 s74, 0
.Lscan_steps:
	s_waitcnt lgkmcnt(1)
	ds_read_b128 v[102:105], v2 offset:2128
	ds_read_b128 v[90:93], v2 offset:1360
	ds_read_b128 v[94:97], v2 offset:1616
	ds_read_b32 v110, v3 offset:2640
	ds_read_b128 v[98:101], v2 offset:1872
	ds_read_b128 v[106:109], v2 offset:2384
	ds_read_b64 v[112:113], v4 offset:2704
	v_pk_mul_f32 v[32:33], v[20:21], v[68:69]
	v_pk_mul_f32 v[34:35], v[8:9], v[68:69]
	v_pk_fma_f32 v[32:33], v[22:23], v[70:71], v[32:33]
	v_pk_fma_f32 v[34:35], v[70:71], v[10:11], v[34:35]
	v_pk_mul_f32 v[36:37], v[12:13], v[68:69]
	v_add_f32_e32 v40, v32, v33
	v_add_f32_e32 v41, v34, v35
	v_pk_mul_f32 v[38:39], v[14:15], v[70:71]
	v_add_f32_dpp v40, v40, v40 row_ror:8 row_mask:0xf bank_mask:0xf bound_ctrl:1
	v_add_f32_dpp v41, v41, v41 row_ror:8 row_mask:0xf bank_mask:0xf bound_ctrl:1
	v_pk_fma_f32 v[36:37], v[28:29], v[16:17], v[36:37] op_sel_hi:[0,1,1]
	v_add_f32_dpp v40, v40, v40 row_ror:4 row_mask:0xf bank_mask:0xf bound_ctrl:1
	v_add_f32_dpp v41, v41, v41 row_ror:4 row_mask:0xf bank_mask:0xf bound_ctrl:1
	v_pk_fma_f32 v[38:39], v[28:29], v[18:19], v[38:39] op_sel_hi:[0,1,1]
	v_add_f32_dpp v40, v40, v40 row_ror:2 row_mask:0xf bank_mask:0xf bound_ctrl:1
	v_add_f32_dpp v41, v41, v41 row_ror:2 row_mask:0xf bank_mask:0xf bound_ctrl:1
	v_mul_f32_e32 v72, v28, v31
	v_add_f32_dpp v40, v40, v40 row_ror:1 row_mask:0xf bank_mask:0xf bound_ctrl:1
	v_add_f32_dpp v41, v41, v41 row_ror:1 row_mask:0xf bank_mask:0xf bound_ctrl:1
	v_pk_fma_f32 v[68:69], v[24:25], v[40:41], v[36:37] op_sel_hi:[1,0,1]
	v_pk_fma_f32 v[70:71], v[26:27], v[40:41], v[38:39] op_sel_hi:[1,0,1]
	v_fma_f32 v73, v40, v30, v41
	v_add_f32_e32 v73, v72, v73
	ds_write_b32 v5, v73 offset:0
	s_waitcnt lgkmcnt(1)
	ds_read_b128 v[20:23], v2 offset:3488
	ds_read_b128 v[8:11], v2 offset:2720
	ds_read_b128 v[12:15], v2 offset:2976
	ds_read_b32 v28, v3 offset:4000
	ds_read_b128 v[16:19], v2 offset:3232
	ds_read_b128 v[24:27], v2 offset:3744
	ds_read_b64 v[30:31], v4 offset:4064
	v_pk_mul_f32 v[32:33], v[102:103], v[68:69]
	v_pk_mul_f32 v[34:35], v[90:91], v[68:69]
	v_pk_fma_f32 v[32:33], v[104:105], v[70:71], v[32:33]
	v_pk_fma_f32 v[34:35], v[70:71], v[92:93], v[34:35]
	v_pk_mul_f32 v[36:37], v[94:95], v[68:69]
	v_add_f32_e32 v40, v32, v33
	v_add_f32_e32 v41, v34, v35
	v_pk_mul_f32 v[38:39], v[96:97], v[70:71]
	v_add_f32_dpp v40, v40, v40 row_ror:8 row_mask:0xf bank_mask:0xf bound_ctrl:1
	v_add_f32_dpp v41, v41, v41 row_ror:8 row_mask:0xf bank_mask:0xf bound_ctrl:1
	v_pk_fma_f32 v[36:37], v[110:111], v[98:99], v[36:37] op_sel_hi:[0,1,1]
	v_add_f32_dpp v40, v40, v40 row_ror:4 row_mask:0xf bank_mask:0xf bound_ctrl:1
	v_add_f32_dpp v41, v41, v41 row_ror:4 row_mask:0xf bank_mask:0xf bound_ctrl:1
	v_pk_fma_f32 v[38:39], v[110:111], v[100:101], v[38:39] op_sel_hi:[0,1,1]
	v_add_f32_dpp v40, v40, v40 row_ror:2 row_mask:0xf bank_mask:0xf bound_ctrl:1
	v_add_f32_dpp v41, v41, v41 row_ror:2 row_mask:0xf bank_mask:0xf bound_ctrl:1
	v_mul_f32_e32 v72, v110, v113
	v_add_f32_dpp v40, v40, v40 row_ror:1 row_mask:0xf bank_mask:0xf bound_ctrl:1
	v_add_f32_dpp v41, v41, v41 row_ror:1 row_mask:0xf bank_mask:0xf bound_ctrl:1
	v_pk_fma_f32 v[68:69], v[106:107], v[40:41], v[36:37] op_sel_hi:[1,0,1]
	v_pk_fma_f32 v[70:71], v[108:109], v[40:41], v[38:39] op_sel_hi:[1,0,1]
	v_fma_f32 v73, v40, v112, v41
	v_add_f32_e32 v73, v72, v73
	ds_write_b32 v5, v73 offset:64
	s_waitcnt lgkmcnt(1)
	ds_read_b128 v[102:105], v2 offset:4848
	ds_read_b128 v[90:93], v2 offset:4080
	ds_read_b128 v[94:97], v2 offset:4336
	ds_read_b32 v110, v3 offset:5360
	ds_read_b128 v[98:101], v2 offset:4592
	ds_read_b128 v[106:109], v2 offset:5104
	ds_read_b64 v[112:113], v4 offset:5424
	v_pk_mul_f32 v[32:33], v[20:21], v[68:69]
	v_pk_mul_f32 v[34:35], v[8:9], v[68:69]
	v_pk_fma_f32 v[32:33], v[22:23], v[70:71], v[32:33]
	v_pk_fma_f32 v[34:35], v[70:71], v[10:11], v[34:35]
	v_pk_mul_f32 v[36:37], v[12:13], v[68:69]
	v_add_f32_e32 v40, v32, v33
	v_add_f32_e32 v41, v34, v35
	v_pk_mul_f32 v[38:39], v[14:15], v[70:71]
	v_add_f32_dpp v40, v40, v40 row_ror:8 row_mask:0xf bank_mask:0xf bound_ctrl:1
	v_add_f32_dpp v41, v41, v41 row_ror:8 row_mask:0xf bank_mask:0xf bound_ctrl:1
	v_pk_fma_f32 v[36:37], v[28:29], v[16:17], v[36:37] op_sel_hi:[0,1,1]
	v_add_f32_dpp v40, v40, v40 row_ror:4 row_mask:0xf bank_mask:0xf bound_ctrl:1
	v_add_f32_dpp v41, v41, v41 row_ror:4 row_mask:0xf bank_mask:0xf bound_ctrl:1
	v_pk_fma_f32 v[38:39], v[28:29], v[18:19], v[38:39] op_sel_hi:[0,1,1]
	v_add_f32_dpp v40, v40, v40 row_ror:2 row_mask:0xf bank_mask:0xf bound_ctrl:1
	v_add_f32_dpp v41, v41, v41 row_ror:2 row_mask:0xf bank_mask:0xf bound_ctrl:1
	v_mul_f32_e32 v72, v28, v31
	v_add_f32_dpp v40, v40, v40 row_ror:1 row_mask:0xf bank_mask:0xf bound_ctrl:1
	v_add_f32_dpp v41, v41, v41 row_ror:1 row_mask:0xf bank_mask:0xf bound_ctrl:1
	v_pk_fma_f32 v[68:69], v[24:25], v[40:41], v[36:37] op_sel_hi:[1,0,1]
	v_pk_fma_f32 v[70:71], v[26:27], v[40:41], v[38:39] op_sel_hi:[1,0,1]
	v_fma_f32 v73, v40, v30, v41
	v_add_f32_e32 v73, v72, v73
	ds_write_b32 v5, v73 offset:128
	s_waitcnt lgkmcnt(1)
; __global__ void __launch_bounds__(NTHR) mega(Params p) {
;     ...
;               for (int st = 0; st < 32; ++st) {
;                 const float* sn = cbuf + ((st + 1) & 31) * 340;
;                 const float4 dr2 = *(const float4*)(sn + 4 * kg), dd2 = *(const float4*)(sn + 64 + 4 * kg);
;                 const float4 kp2 = *(const float4*)(sn + 128 + 4 * kg), nk2 = *(const float4*)(sn + 192 + 4 * kg);
;                 const float4 ka2 = *(const float4*)(sn + 256 + 4 * kg);
;                 const float vv2 = sn[320 + row];
;                 const float2 cc2 = *(const float2*)(sn + 336);
;                 const f32x2 nkA = {nk.x, nk.y}, nkB = {nk.z, nk.w}, drA = {dr.x, dr.y}, drB = {dr.z, dr.w};
;                 const f32x2 ddA = {dd.x, dd.y}, ddB = {dd.z, dd.w}, kpA = {kp.x, kp.y}, kpB = {kp.z, kp.w};
;                 const f32x2 kaA = {ka.x, ka.y}, kaB = {ka.z, ka.w};
;                 const f32x2 v2 = {vv, vv};
;                 f32x2 pa = sA * nkA; pa = sB * nkB + pa;
;                 f32x2 py = sA * drA; py = sB * drB + py;
;                 f32x2 tA = v2 * kpA; tA = sA * ddA + tA;
;                 f32x2 tB = v2 * kpB; tB = sB * ddB + tB;
;                 float sa = row16_sum(pa.x + pa.y);
;                 const float yy = row16_sum(py.x + py.y);
;                 const f32x2 sa2 = {sa, sa};
;                 sA = sa2 * kaA + tA;
;                 sB = sa2 * kaB + tB;
;                 if (kg == 0) yb[st * 16 + row] = yy + sa * cc.x + vv * cc.y;
;                 dr = dr2; dd = dd2; kp = kp2; nk = nk2; ka = ka2; vv = vv2; cc = cc2;
	ds_read_b128 v[20:23], v2 offset:6208
	ds_read_b128 v[8:11], v2 offset:5440
	ds_read_b128 v[12:15], v2 offset:5696
	ds_read_b32 v28, v3 offset:6720
	ds_read_b128 v[16:19], v2 offset:5952
	ds_read_b128 v[24:27], v2 offset:6464
	ds_read_b64 v[30:31], v4 offset:6784
	v_pk_mul_f32 v[32:33], v[102:103], v[68:69]
	v_pk_mul_f32 v[34:35], v[90:91], v[68:69]
	v_pk_fma_f32 v[32:33], v[104:105], v[70:71], v[32:33]
	v_pk_fma_f32 v[34:35], v[70:71], v[92:93], v[34:35]
	v_pk_mul_f32 v[36:37], v[94:95], v[68:69]
	v_add_f32_e32 v40, v32, v33
	v_add_f32_e32 v41, v34, v35
	v_pk_mul_f32 v[38:39], v[96:97], v[70:71]
	v_add_f32_dpp v40, v40, v40 row_ror:8 row_mask:0xf bank_mask:0xf bound_ctrl:1
	v_add_f32_dpp v41, v41, v41 row_ror:8 row_mask:0xf bank_mask:0xf bound_ctrl:1
	v_pk_fma_f32 v[36:37], v[110:111], v[98:99], v[36:37] op_sel_hi:[0,1,1]
	v_add_f32_dpp v40, v40, v40 row_ror:4 row_mask:0xf bank_mask:0xf bound_ctrl:1
	v_add_f32_dpp v41, v41, v41 row_ror:4 row_mask:0xf bank_mask:0xf bound_ctrl:1
	v_pk_fma_f32 v[38:39], v[110:111], v[100:101], v[38:39] op_sel_hi:[0,1,1]
	v_add_f32_dpp v40, v40, v40 row_ror:2 row_mask:0xf bank_mask:0xf bound_ctrl:1
	v_add_f32_dpp v41, v41, v41 row_ror:2 row_mask:0xf bank_mask:0xf bound_ctrl:1
	v_mul_f32_e32 v72, v110, v113
	v_add_f32_dpp v40, v40, v40 row_ror:1 row_mask:0xf bank_mask:0xf bound_ctrl:1
	v_add_f32_dpp v41, v41, v41 row_ror:1 row_mask:0xf bank_mask:0xf bound_ctrl:1
	v_pk_fma_f32 v[68:69], v[106:107], v[40:41], v[36:37] op_sel_hi:[1,0,1]
	v_pk_fma_f32 v[70:71], v[108:109], v[40:41], v[38:39] op_sel_hi:[1,0,1]
	v_fma_f32 v73, v40, v112, v41
	v_add_f32_e32 v73, v72, v73
	ds_write_b32 v5, v73 offset:192
	s_waitcnt lgkmcnt(1)
	ds_read_b128 v[102:105], v2 offset:7568
	ds_read_b128 v[90:93], v2 offset:6800
	ds_read_b128 v[94:97], v2 offset:7056
	ds_read_b32 v110, v3 offset:8080
	ds_read_b128 v[98:101], v2 offset:7312
	ds_read_b128 v[106:109], v2 offset:7824
	ds_read_b64 v[112:113], v4 offset:8144
	v_pk_mul_f32 v[32:33], v[20:21], v[68:69]
	v_pk_mul_f32 v[34:35], v[8:9], v[68:69]
	v_pk_fma_f32 v[32:33], v[22:23], v[70:71], v[32:33]
	v_pk_fma_f32 v[34:35], v[70:71], v[10:11], v[34:35]
	v_pk_mul_f32 v[36:37], v[12:13], v[68:69]
	v_add_f32_e32 v40, v32, v33
	v_add_f32_e32 v41, v34, v35
	v_pk_mul_f32 v[38:39], v[14:15], v[70:71]
	v_add_f32_dpp v40, v40, v40 row_ror:8 row_mask:0xf bank_mask:0xf bound_ctrl:1
	v_add_f32_dpp v41, v41, v41 row_ror:8 row_mask:0xf bank_mask:0xf bound_ctrl:1
	v_pk_fma_f32 v[36:37], v[28:29], v[16:17], v[36:37] op_sel_hi:[0,1,1]
	v_add_f32_dpp v40, v40, v40 row_ror:4 row_mask:0xf bank_mask:0xf bound_ctrl:1
	v_add_f32_dpp v41, v41, v41 row_ror:4 row_mask:0xf bank_mask:0xf bound_ctrl:1
	v_pk_fma_f32 v[38:39], v[28:29], v[18:19], v[38:39] op_sel_hi:[0,1,1]
	v_add_f32_dpp v40, v40, v40 row_ror:2 row_mask:0xf bank_mask:0xf bound_ctrl:1
	v_add_f32_dpp v41, v41, v41 row_ror:2 row_mask:0xf bank_mask:0xf bound_ctrl:1
	v_mul_f32_e32 v72, v28, v31
	v_add_f32_dpp v40, v40, v40 row_ror:1 row_mask:0xf bank_mask:0xf bound_ctrl:1
	v_add_f32_dpp v41, v41, v41 row_ror:1 row_mask:0xf bank_mask:0xf bound_ctrl:1
	v_pk_fma_f32 v[68:69], v[24:25], v[40:41], v[36:37] op_sel_hi:[1,0,1]
	v_pk_fma_f32 v[70:71], v[26:27], v[40:41], v[38:39] op_sel_hi:[1,0,1]
	v_fma_f32 v73, v40, v30, v41
	v_add_f32_e32 v73, v72, v73
	ds_write_b32 v5, v73 offset:256
	s_waitcnt lgkmcnt(1)
	ds_read_b128 v[20:23], v2 offset:8928
	ds_read_b128 v[8:11], v2 offset:8160
	ds_read_b128 v[12:15], v2 offset:8416
	ds_read_b32 v28, v3 offset:9440
	ds_read_b128 v[16:19], v2 offset:8672
	ds_read_b128 v[24:27], v2 offset:9184
	ds_read_b64 v[30:31], v4 offset:9504
	v_pk_mul_f32 v[32:33], v[102:103], v[68:69]
	v_pk_mul_f32 v[34:35], v[90:91], v[68:69]
	v_pk_fma_f32 v[32:33], v[104:105], v[70:71], v[32:33]
	v_pk_fma_f32 v[34:35], v[70:71], v[92:93], v[34:35]
	v_pk_mul_f32 v[36:37], v[94:95], v[68:69]
	v_add_f32_e32 v40, v32, v33
	v_add_f32_e32 v41, v34, v35
	v_pk_mul_f32 v[38:39], v[96:97], v[70:71]
	v_add_f32_dpp v40, v40, v40 row_ror:8 row_mask:0xf bank_mask:0xf bound_ctrl:1
	v_add_f32_dpp v41, v41, v41 row_ror:8 row_mask:0xf bank_mask:0xf bound_ctrl:1
	v_pk_fma_f32 v[36:37], v[110:111], v[98:99], v[36:37] op_sel_hi:[0,1,1]
	v_add_f32_dpp v40, v40, v40 row_ror:4 row_mask:0xf bank_mask:0xf bound_ctrl:1
	v_add_f32_dpp v41, v41, v41 row_ror:4 row_mask:0xf bank_mask:0xf bound_ctrl:1
	v_pk_fma_f32 v[38:39], v[110:111], v[100:101], v[38:39] op_sel_hi:[0,1,1]
	v_add_f32_dpp v40, v40, v40 row_ror:2 row_mask:0xf bank_mask:0xf bound_ctrl:1
	v_add_f32_dpp v41, v41, v41 row_ror:2 row_mask:0xf bank_mask:0xf bound_ctrl:1
	v_mul_f32_e32 v72, v110, v113
	v_add_f32_dpp v40, v40, v40 row_ror:1 row_mask:0xf bank_mask:0xf bound_ctrl:1
	v_add_f32_dpp v41, v41, v41 row_ror:1 row_mask:0xf bank_mask:0xf bound_ctrl:1
	v_pk_fma_f32 v[68:69], v[106:107], v[40:41], v[36:37] op_sel_hi:[1,0,1]
	v_pk_fma_f32 v[70:71], v[108:109], v[40:41], v[38:39] op_sel_hi:[1,0,1]
	v_fma_f32 v73, v40, v112, v41
	v_add_f32_e32 v73, v72, v73
	ds_write_b32 v5, v73 offset:320
	s_waitcnt lgkmcnt(1)
; __global__ void __launch_bounds__(NTHR) mega(Params p) {
;     ...
;               for (int st = 0; st < 32; ++st) {
;                 const float* sn = cbuf + ((st + 1) & 31) * 340;
;                 const float4 dr2 = *(const float4*)(sn + 4 * kg), dd2 = *(const float4*)(sn + 64 + 4 * kg);
;                 const float4 kp2 = *(const float4*)(sn + 128 + 4 * kg), nk2 = *(const float4*)(sn + 192 + 4 * kg);
;                 const float4 ka2 = *(const float4*)(sn + 256 + 4 * kg);
;                 const float vv2 = sn[320 + row];
;                 const float2 cc2 = *(const float2*)(sn + 336);
;                 const f32x2 nkA = {nk.x, nk.y}, nkB = {nk.z, nk.w}, drA = {dr.x, dr.y}, drB = {dr.z, dr.w};
;                 const f32x2 ddA = {dd.x, dd.y}, ddB = {dd.z, dd.w}, kpA = {kp.x, kp.y}, kpB = {kp.z, kp.w};
;                 const f32x2 kaA = {ka.x, ka.y}, kaB = {ka.z, ka.w};
;                 const f32x2 v2 = {vv, vv};
;                 f32x2 pa = sA * nkA; pa = sB * nkB + pa;
;                 f32x2 py = sA * drA; py = sB * drB + py;
;                 f32x2 tA = v2 * kpA; tA = sA * ddA + tA;
;                 f32x2 tB = v2 * kpB; tB = sB * ddB + tB;
;                 float sa = row16_sum(pa.x + pa.y);
;                 const float yy = row16_sum(py.x + py.y);
;                 const f32x2 sa2 = {sa, sa};
;                 sA = sa2 * kaA + tA;
;                 sB = sa2 * kaB + tB;
;                 if (kg == 0) yb[st * 16 + row] = yy + sa * cc.x + vv * cc.y;
;                 dr = dr2; dd = dd2; kp = kp2; nk = nk2; ka = ka2; vv = vv2; cc = cc2;
;               }
;               s0 = sA.x; s1 = sA.y; s2 = sB.x; s3 = sB.y;
	ds_read_b128 v[102:105], v2 offset:10288
	ds_read_b128 v[90:93], v2 offset:9520
	ds_read_b128 v[94:97], v2 offset:9776
	ds_read_b32 v110, v3 offset:10800
	ds_read_b128 v[98:101], v2 offset:10032
	ds_read_b128 v[106:109], v2 offset:10544
	ds_read_b64 v[112:113], v4 offset:10864
	v_pk_mul_f32 v[32:33], v[20:21], v[68:69]
	v_pk_mul_f32 v[34:35], v[8:9], v[68:69]
	v_pk_fma_f32 v[32:33], v[22:23], v[70:71], v[32:33]
	v_pk_fma_f32 v[34:35], v[70:71], v[10:11], v[34:35]
	v_pk_mul_f32 v[36:37], v[12:13], v[68:69]
	v_add_f32_e32 v40, v32, v33
	v_add_f32_e32 v41, v34, v35
	v_pk_mul_f32 v[38:39], v[14:15], v[70:71]
	v_add_f32_dpp v40, v40, v40 row_ror:8 row_mask:0xf bank_mask:0xf bound_ctrl:1
	v_add_f32_dpp v41, v41, v41 row_ror:8 row_mask:0xf bank_mask:0xf bound_ctrl:1
	v_pk_fma_f32 v[36:37], v[28:29], v[16:17], v[36:37] op_sel_hi:[0,1,1]
	v_add_f32_dpp v40, v40, v40 row_ror:4 row_mask:0xf bank_mask:0xf bound_ctrl:1
	v_add_f32_dpp v41, v41, v41 row_ror:4 row_mask:0xf bank_mask:0xf bound_ctrl:1
	v_pk_fma_f32 v[38:39], v[28:29], v[18:19], v[38:39] op_sel_hi:[0,1,1]
	v_add_f32_dpp v40, v40, v40 row_ror:2 row_mask:0xf bank_mask:0xf bound_ctrl:1
	v_add_f32_dpp v41, v41, v41 row_ror:2 row_mask:0xf bank_mask:0xf bound_ctrl:1
	v_mul_f32_e32 v72, v28, v31
	v_add_f32_dpp v40, v40, v40 row_ror:1 row_mask:0xf bank_mask:0xf bound_ctrl:1
	v_add_f32_dpp v41, v41, v41 row_ror:1 row_mask:0xf bank_mask:0xf bound_ctrl:1
	v_pk_fma_f32 v[68:69], v[24:25], v[40:41], v[36:37] op_sel_hi:[1,0,1]
	v_pk_fma_f32 v[70:71], v[26:27], v[40:41], v[38:39] op_sel_hi:[1,0,1]
	v_fma_f32 v73, v40, v30, v41
	v_add_f32_e32 v73, v72, v73
	ds_write_b32 v5, v73 offset:384
	s_waitcnt lgkmcnt(1)
	ds_read_b128 v[20:23], v2 offset:11648
	ds_read_b128 v[8:11], v2 offset:10880
	ds_read_b128 v[12:15], v2 offset:11136
	ds_read_b32 v28, v3 offset:12160
	ds_read_b128 v[16:19], v2 offset:11392
	ds_read_b128 v[24:27], v2 offset:11904
	ds_read_b64 v[30:31], v4 offset:12224
	v_pk_mul_f32 v[32:33], v[102:103], v[68:69]
	v_pk_mul_f32 v[34:35], v[90:91], v[68:69]
	v_pk_fma_f32 v[32:33], v[104:105], v[70:71], v[32:33]
	v_pk_fma_f32 v[34:35], v[70:71], v[92:93], v[34:35]
	v_pk_mul_f32 v[36:37], v[94:95], v[68:69]
	v_add_f32_e32 v40, v32, v33
	v_add_f32_e32 v41, v34, v35
	v_pk_mul_f32 v[38:39], v[96:97], v[70:71]
	v_add_f32_dpp v40, v40, v40 row_ror:8 row_mask:0xf bank_mask:0xf bound_ctrl:1
	v_add_f32_dpp v41, v41, v41 row_ror:8 row_mask:0xf bank_mask:0xf bound_ctrl:1
	v_pk_fma_f32 v[36:37], v[110:111], v[98:99], v[36:37] op_sel_hi:[0,1,1]
	v_add_f32_dpp v40, v40, v40 row_ror:4 row_mask:0xf bank_mask:0xf bound_ctrl:1
	v_add_f32_dpp v41, v41, v41 row_ror:4 row_mask:0xf bank_mask:0xf bound_ctrl:1
	v_pk_fma_f32 v[38:39], v[110:111], v[100:101], v[38:39] op_sel_hi:[0,1,1]
	v_add_f32_dpp v40, v40, v40 row_ror:2 row_mask:0xf bank_mask:0xf bound_ctrl:1
	v_add_f32_dpp v41, v41, v41 row_ror:2 row_mask:0xf bank_mask:0xf bound_ctrl:1
	v_mul_f32_e32 v72, v110, v113
	v_add_f32_dpp v40, v40, v40 row_ror:1 row_mask:0xf bank_mask:0xf bound_ctrl:1
	v_add_f32_dpp v41, v41, v41 row_ror:1 row_mask:0xf bank_mask:0xf bound_ctrl:1
	v_pk_fma_f32 v[68:69], v[106:107], v[40:41], v[36:37] op_sel_hi:[1,0,1]
	v_pk_fma_f32 v[70:71], v[108:109], v[40:41], v[38:39] op_sel_hi:[1,0,1]
	v_fma_f32 v73, v40, v112, v41
	v_add_f32_e32 v73, v72, v73
	ds_write_b32 v5, v73 offset:448
	v_add_u32_e32 v2, 10880, v2
	v_add_u32_e32 v3, 10880, v3
	v_add_u32_e32 v4, 10880, v4
	v_add_u32_e32 v5, 512, v5
	s_add_i32 s74, s74, 1
	s_cmp_lg_u32 s74, 4
	s_cbranch_scc1 .Lscan_steps
